# v38 + up-proj GEMM epilogue: the eight row-scale loads issued as one batch with a single wait (no per-row-group vmcnt(0) drains)
# baseline (speedup 1.0000x reference)
; __device__ __forceinline__ unsigned cvt_pk_bf16(float lo, float hi) { unsigned r; asm volatile("v_cvt_pk_bf16_f32 %0, %1, %2" : "=v"(r) : "v"(lo), "v"(hi)); return r; }
;     DI void operator()(const f32x4 (&acc)[2][2][4][2], const Unit& u, int wr, int wc, int fr, int fq) const {
;         const int row0 = u.pm * 256 + wr * 64 + fr, col0 = u.pn * 256 + wc * 32 + 8 * fq;
; #pragma unroll
;         for (int ai = 0; ai < 2; ++ai)
; #pragma unroll
;             for (int m = 0; m < 4; ++m) { const int row = row0 + ai * 128 + m * 16; const float s = rsqrtf(ssum2[row] * (1.f / 1024.f) + EPS);
;                 bf16_t* rowp = U + (size_t)row * 4096 + col0;
; #pragma unroll
;                 for (int bj = 0; bj < 2; ++bj) { f32x4 v0 = acc[ai][bj][m][0] * s, v1 = acc[ai][bj][m][1] * s;
; #pragma unroll
;                     for (int j = 0; j < 4; ++j) { const float a = fmaxf(v0[j], 0.f), b = fmaxf(v1[j], 0.f); v0[j] = a * a; v1[j] = b * b; }
;                     u32x4 w; w.x = cvt_pk_bf16(v0[0], v0[1]); w.y = cvt_pk_bf16(v0[2], v0[3]); w.z = cvt_pk_bf16(v1[0], v1[1]); w.w = cvt_pk_bf16(v1[2], v1[3]);
;                     __builtin_nontemporal_store(w, (u32x4*)(rowp + bj * 128)); } }
;     }
.LBB0_2070:
	v_lshl_add_u32 v148, s6, 8, v152
	v_ashrrev_i32_e32 v149, 31, v148
	v_lshl_add_u64 v[144:145], v[148:149], 2, s[16:17]
	global_load_dword v159, v[144:145], off
	global_load_dword v226, v[144:145], off offset:64
	global_load_dword v227, v[144:145], off offset:128
	global_load_dword v228, v[144:145], off offset:192
	global_load_dword v229, v[144:145], off offset:512
	global_load_dword v230, v[144:145], off offset:576
	global_load_dword v231, v[144:145], off offset:640
	global_load_dword v232, v[144:145], off offset:704
	v_lshl_or_b32 v146, s7, 8, v154
	v_ashrrev_i32_e32 v147, 31, v146
	v_lshlrev_b64 v[150:151], 1, v[146:147]
	v_lshlrev_b64 v[162:163], 13, v[148:149]
	v_or_b32_e32 v160, 16, v148
	v_ashrrev_i32_e32 v161, 31, v160
	s_waitcnt vmcnt(0)
	v_fmamk_f32 v146, v159, 0x3a800000, v158
	v_mul_f32_e32 v147, 0x4b800000, v146
	v_cmp_gt_f32_e32 vcc, s62, v146
	s_nop 1
	v_cndmask_b32_e32 v146, v146, v147, vcc
	v_rsq_f32_e32 v149, v146
	v_lshl_add_u64 v[146:147], s[14:15], 0, v[162:163]
	v_lshl_add_u64 v[146:147], v[146:147], 0, v[150:151]
	v_lshl_add_u64 v[162:163], v[160:161], 2, s[16:17]
	v_mul_f32_e32 v159, 0x45800000, v149
	v_cndmask_b32_e32 v164, v149, v159, vcc
	v_mul_f32_e32 v126, v126, v164
	v_mul_f32_e32 v127, v127, v164
	v_mul_f32_e32 v124, v124, v164
	v_mul_f32_e32 v125, v125, v164
	v_mul_f32_e32 v122, v122, v164
	v_mul_f32_e32 v123, v123, v164
	v_mul_f32_e32 v120, v120, v164
	v_mul_f32_e32 v121, v121, v164
	v_mul_f32_e32 v114, v114, v164
	v_mul_f32_e32 v115, v115, v164
	v_mul_f32_e32 v112, v112, v164
	v_mul_f32_e32 v113, v113, v164
	v_mul_f32_e32 v118, v118, v164
	v_mul_f32_e32 v119, v119, v164
	v_mul_f32_e32 v116, v116, v164
	v_mul_f32_e32 v117, v117, v164
	v_max_f32_e32 v124, 0, v124
	v_max_f32_e32 v120, 0, v120
	v_max_f32_e32 v125, 0, v125
	v_max_f32_e32 v121, 0, v121
	v_max_f32_e32 v126, 0, v126
	v_max_f32_e32 v122, 0, v122
	v_max_f32_e32 v127, 0, v127
	v_max_f32_e32 v123, 0, v123
	v_max_f32_e32 v112, 0, v112
	v_max_f32_e32 v113, 0, v113
	v_max_f32_e32 v114, 0, v114
	v_max_f32_e32 v115, 0, v115
	v_max_f32_e32 v116, 0, v116
	v_max_f32_e32 v117, 0, v117
	v_max_f32_e32 v118, 0, v118
	v_max_f32_e32 v119, 0, v119
	v_mul_f32_e32 v124, v124, v124
	v_mul_f32_e32 v120, v120, v120
	v_mul_f32_e32 v125, v125, v125
	v_mul_f32_e32 v121, v121, v121
	v_mul_f32_e32 v126, v126, v126
	v_mul_f32_e32 v122, v122, v122
	v_mul_f32_e32 v127, v127, v127
	v_mul_f32_e32 v123, v123, v123
	v_mul_f32_e32 v149, v112, v112
	v_mul_f32_e32 v159, v113, v113
	v_mul_f32_e32 v164, v114, v114
	v_mul_f32_e32 v165, v115, v115
	v_cvt_pk_bf16_f32 v112, v124, v125
	v_cvt_pk_bf16_f32 v113, v126, v127
	v_cvt_pk_bf16_f32 v114, v120, v121
	v_cvt_pk_bf16_f32 v115, v122, v123
	v_mul_f32_e32 v116, v116, v116
	v_mul_f32_e32 v117, v117, v117
	v_mul_f32_e32 v118, v118, v118
	v_mul_f32_e32 v119, v119, v119
	global_store_dwordx4 v[146:147], v[112:115], off nt
	s_nop 1
	v_cvt_pk_bf16_f32 v112, v116, v117
	v_cvt_pk_bf16_f32 v113, v118, v119
	v_cvt_pk_bf16_f32 v114, v149, v159
	v_cvt_pk_bf16_f32 v115, v164, v165
	global_store_dwordx4 v[146:147], v[112:115], off offset:256 nt
	s_nop 0
	s_nop 0
	v_fmamk_f32 v116, v226, 0x3a800000, v158
	v_mul_f32_e32 v117, 0x4b800000, v116
	v_cmp_gt_f32_e32 vcc, s62, v116
	v_lshlrev_b64 v[114:115], 13, v[160:161]
	v_or_b32_e32 v112, 32, v148
	v_cndmask_b32_e32 v116, v116, v117, vcc
	v_rsq_f32_e32 v118, v116
	v_lshl_add_u64 v[114:115], s[14:15], 0, v[114:115]
	v_ashrrev_i32_e32 v113, 31, v112
	v_lshl_add_u64 v[114:115], v[114:115], 0, v[150:151]
	v_mul_f32_e32 v119, 0x45800000, v118
	v_cndmask_b32_e32 v118, v118, v119, vcc
	v_mul_f32_e32 v110, v110, v118
	v_mul_f32_e32 v111, v111, v118
	v_mul_f32_e32 v108, v108, v118
	v_mul_f32_e32 v109, v109, v118
	v_mul_f32_e32 v106, v106, v118
	v_mul_f32_e32 v107, v107, v118
	v_mul_f32_e32 v104, v104, v118
	v_mul_f32_e32 v105, v105, v118
	v_mul_f32_e32 v98, v98, v118
	v_mul_f32_e32 v99, v99, v118
	v_mul_f32_e32 v96, v96, v118
	v_mul_f32_e32 v97, v97, v118
	v_mul_f32_e32 v102, v102, v118
	v_mul_f32_e32 v103, v103, v118
	v_mul_f32_e32 v100, v100, v118
	v_mul_f32_e32 v101, v101, v118
	v_max_f32_e32 v108, 0, v108
	v_max_f32_e32 v104, 0, v104
	v_max_f32_e32 v109, 0, v109
	v_max_f32_e32 v105, 0, v105
	v_max_f32_e32 v110, 0, v110
	v_max_f32_e32 v106, 0, v106
	v_max_f32_e32 v111, 0, v111
	v_max_f32_e32 v107, 0, v107
	v_max_f32_e32 v96, 0, v96
	v_max_f32_e32 v97, 0, v97
	v_max_f32_e32 v98, 0, v98
	v_max_f32_e32 v99, 0, v99
	v_max_f32_e32 v100, 0, v100
	v_max_f32_e32 v101, 0, v101
	v_max_f32_e32 v102, 0, v102
	v_max_f32_e32 v103, 0, v103
	v_mul_f32_e32 v108, v108, v108
	v_mul_f32_e32 v104, v104, v104
	v_mul_f32_e32 v109, v109, v109
	v_mul_f32_e32 v105, v105, v105
	v_mul_f32_e32 v110, v110, v110
	v_mul_f32_e32 v106, v106, v106
	v_mul_f32_e32 v111, v111, v111
	v_mul_f32_e32 v107, v107, v107
	v_mul_f32_e32 v118, v96, v96
	v_mul_f32_e32 v119, v97, v97
	v_mul_f32_e32 v120, v98, v98
	v_mul_f32_e32 v121, v99, v99
	v_cvt_pk_bf16_f32 v96, v108, v109
	v_cvt_pk_bf16_f32 v97, v110, v111
	v_cvt_pk_bf16_f32 v98, v104, v105
	v_cvt_pk_bf16_f32 v99, v106, v107
	v_lshl_add_u64 v[116:117], v[112:113], 2, s[16:17]
	v_mul_f32_e32 v100, v100, v100
	v_mul_f32_e32 v101, v101, v101
	v_mul_f32_e32 v102, v102, v102
	v_mul_f32_e32 v103, v103, v103
	global_store_dwordx4 v[114:115], v[96:99], off nt
	s_nop 1
	v_cvt_pk_bf16_f32 v96, v100, v101
	v_cvt_pk_bf16_f32 v97, v102, v103
	v_cvt_pk_bf16_f32 v98, v118, v119
	v_cvt_pk_bf16_f32 v99, v120, v121
	global_store_dwordx4 v[114:115], v[96:99], off offset:256 nt
	s_nop 0
	s_nop 0
	v_fmamk_f32 v100, v227, 0x3a800000, v158
	v_mul_f32_e32 v101, 0x4b800000, v100
	v_cmp_gt_f32_e32 vcc, s62, v100
; __device__ __forceinline__ unsigned cvt_pk_bf16(float lo, float hi) { unsigned r; asm volatile("v_cvt_pk_bf16_f32 %0, %1, %2" : "=v"(r) : "v"(lo), "v"(hi)); return r; }
;     DI void operator()(const f32x4 (&acc)[2][2][4][2], const Unit& u, int wr, int wc, int fr, int fq) const {
;         const int row0 = u.pm * 256 + wr * 64 + fr, col0 = u.pn * 256 + wc * 32 + 8 * fq;
; #pragma unroll
;         for (int ai = 0; ai < 2; ++ai)
; #pragma unroll
;             for (int m = 0; m < 4; ++m) { const int row = row0 + ai * 128 + m * 16; const float s = rsqrtf(ssum2[row] * (1.f / 1024.f) + EPS);
;                 bf16_t* rowp = U + (size_t)row * 4096 + col0;
; #pragma unroll
;                 for (int bj = 0; bj < 2; ++bj) { f32x4 v0 = acc[ai][bj][m][0] * s, v1 = acc[ai][bj][m][1] * s;
; #pragma unroll
;                     for (int j = 0; j < 4; ++j) { const float a = fmaxf(v0[j], 0.f), b = fmaxf(v1[j], 0.f); v0[j] = a * a; v1[j] = b * b; }
;                     u32x4 w; w.x = cvt_pk_bf16(v0[0], v0[1]); w.y = cvt_pk_bf16(v0[2], v0[3]); w.z = cvt_pk_bf16(v1[0], v1[1]); w.w = cvt_pk_bf16(v1[2], v1[3]);
;                     __builtin_nontemporal_store(w, (u32x4*)(rowp + bj * 128)); } }
;     }
	v_lshlrev_b64 v[98:99], 13, v[112:113]
	v_or_b32_e32 v96, 48, v148
	v_cndmask_b32_e32 v100, v100, v101, vcc
	v_rsq_f32_e32 v102, v100
	v_lshl_add_u64 v[98:99], s[14:15], 0, v[98:99]
	v_ashrrev_i32_e32 v97, 31, v96
	v_lshl_add_u64 v[98:99], v[98:99], 0, v[150:151]
	v_mul_f32_e32 v103, 0x45800000, v102
	v_cndmask_b32_e32 v102, v102, v103, vcc
	v_mul_f32_e32 v94, v94, v102
	v_mul_f32_e32 v95, v95, v102
	v_mul_f32_e32 v92, v92, v102
	v_mul_f32_e32 v93, v93, v102
	v_mul_f32_e32 v90, v90, v102
	v_mul_f32_e32 v91, v91, v102
	v_mul_f32_e32 v88, v88, v102
	v_mul_f32_e32 v89, v89, v102
	v_mul_f32_e32 v82, v82, v102
	v_mul_f32_e32 v83, v83, v102
	v_mul_f32_e32 v80, v80, v102
	v_mul_f32_e32 v81, v81, v102
	v_mul_f32_e32 v86, v86, v102
	v_mul_f32_e32 v87, v87, v102
	v_mul_f32_e32 v84, v84, v102
	v_mul_f32_e32 v85, v85, v102
	v_max_f32_e32 v92, 0, v92
	v_max_f32_e32 v88, 0, v88
	v_max_f32_e32 v93, 0, v93
	v_max_f32_e32 v89, 0, v89
	v_max_f32_e32 v94, 0, v94
	v_max_f32_e32 v90, 0, v90
	v_max_f32_e32 v95, 0, v95
	v_max_f32_e32 v91, 0, v91
	v_max_f32_e32 v80, 0, v80
	v_max_f32_e32 v81, 0, v81
	v_max_f32_e32 v82, 0, v82
	v_max_f32_e32 v83, 0, v83
	v_max_f32_e32 v84, 0, v84
	v_max_f32_e32 v85, 0, v85
	v_max_f32_e32 v86, 0, v86
	v_max_f32_e32 v87, 0, v87
	v_mul_f32_e32 v92, v92, v92
	v_mul_f32_e32 v88, v88, v88
	v_mul_f32_e32 v93, v93, v93
	v_mul_f32_e32 v89, v89, v89
	v_mul_f32_e32 v94, v94, v94
	v_mul_f32_e32 v90, v90, v90
	v_mul_f32_e32 v95, v95, v95
	v_mul_f32_e32 v91, v91, v91
	v_mul_f32_e32 v102, v80, v80
	v_mul_f32_e32 v103, v81, v81
	v_mul_f32_e32 v104, v82, v82
	v_mul_f32_e32 v105, v83, v83
	v_cvt_pk_bf16_f32 v80, v92, v93
	v_cvt_pk_bf16_f32 v81, v94, v95
	v_cvt_pk_bf16_f32 v82, v88, v89
	v_cvt_pk_bf16_f32 v83, v90, v91
	v_lshl_add_u64 v[100:101], v[96:97], 2, s[16:17]
	v_mul_f32_e32 v84, v84, v84
	v_mul_f32_e32 v85, v85, v85
	v_mul_f32_e32 v86, v86, v86
	v_mul_f32_e32 v87, v87, v87
	global_store_dwordx4 v[98:99], v[80:83], off nt
	s_nop 1
	v_cvt_pk_bf16_f32 v80, v84, v85
	v_cvt_pk_bf16_f32 v81, v86, v87
	v_cvt_pk_bf16_f32 v82, v102, v103
	v_cvt_pk_bf16_f32 v83, v104, v105
	global_store_dwordx4 v[98:99], v[80:83], off offset:256 nt
	s_nop 0
	s_nop 0
	v_fmamk_f32 v80, v228, 0x3a800000, v158
	v_mul_f32_e32 v81, 0x4b800000, v80
	v_cmp_gt_f32_e32 vcc, s62, v80
	s_nop 1
	v_cndmask_b32_e32 v80, v80, v81, vcc
	v_rsq_f32_e32 v82, v80
	v_lshlrev_b64 v[80:81], 13, v[96:97]
	v_lshl_add_u64 v[80:81], s[14:15], 0, v[80:81]
	v_lshl_add_u64 v[80:81], v[80:81], 0, v[150:151]
	v_mul_f32_e32 v83, 0x45800000, v82
	v_cndmask_b32_e32 v82, v82, v83, vcc
	v_mul_f32_e32 v78, v78, v82
	v_mul_f32_e32 v79, v79, v82
	v_mul_f32_e32 v76, v76, v82
	v_mul_f32_e32 v77, v77, v82
	v_mul_f32_e32 v74, v74, v82
	v_mul_f32_e32 v75, v75, v82
	v_mul_f32_e32 v72, v72, v82
	v_mul_f32_e32 v73, v73, v82
	v_mul_f32_e32 v66, v66, v82
	v_mul_f32_e32 v67, v67, v82
	v_mul_f32_e32 v64, v64, v82
	v_mul_f32_e32 v65, v65, v82
	v_mul_f32_e32 v70, v70, v82
	v_mul_f32_e32 v71, v71, v82
	v_mul_f32_e32 v68, v68, v82
	v_mul_f32_e32 v69, v69, v82
	v_max_f32_e32 v76, 0, v76
	v_max_f32_e32 v72, 0, v72
	v_max_f32_e32 v77, 0, v77
	v_max_f32_e32 v73, 0, v73
	v_max_f32_e32 v78, 0, v78
	v_max_f32_e32 v74, 0, v74
	v_max_f32_e32 v79, 0, v79
	v_max_f32_e32 v75, 0, v75
	v_max_f32_e32 v64, 0, v64
	v_max_f32_e32 v65, 0, v65
	v_max_f32_e32 v66, 0, v66
	v_max_f32_e32 v67, 0, v67
	v_max_f32_e32 v68, 0, v68
	v_max_f32_e32 v69, 0, v69
	v_max_f32_e32 v70, 0, v70
	v_max_f32_e32 v71, 0, v71
	v_mul_f32_e32 v76, v76, v76
	v_mul_f32_e32 v72, v72, v72
	v_mul_f32_e32 v77, v77, v77
	v_mul_f32_e32 v73, v73, v73
	v_mul_f32_e32 v78, v78, v78
	v_mul_f32_e32 v74, v74, v74
	v_mul_f32_e32 v79, v79, v79
	v_mul_f32_e32 v75, v75, v75
	v_mul_f32_e32 v82, v64, v64
	v_mul_f32_e32 v83, v65, v65
	v_mul_f32_e32 v84, v66, v66
	v_mul_f32_e32 v85, v67, v67
	v_cvt_pk_bf16_f32 v64, v76, v77
	v_cvt_pk_bf16_f32 v65, v78, v79
	v_cvt_pk_bf16_f32 v66, v72, v73
	v_cvt_pk_bf16_f32 v67, v74, v75
	v_mul_f32_e32 v68, v68, v68
	v_mul_f32_e32 v69, v69, v69
	v_mul_f32_e32 v70, v70, v70
	v_mul_f32_e32 v71, v71, v71
	global_store_dwordx4 v[80:81], v[64:67], off nt
	s_nop 1
	v_cvt_pk_bf16_f32 v64, v68, v69
	v_cvt_pk_bf16_f32 v65, v70, v71
	v_cvt_pk_bf16_f32 v66, v82, v83
	v_cvt_pk_bf16_f32 v67, v84, v85
	global_store_dwordx4 v[80:81], v[64:67], off offset:256 nt
	s_nop 0
	s_nop 0
	v_lshl_add_u64 v[64:65], v[146:147], 0, s[20:21]
	s_nop 0
	v_fmamk_f32 v66, v229, 0x3a800000, v158
	v_mul_f32_e32 v67, 0x4b800000, v66
	v_cmp_gt_f32_e32 vcc, s62, v66
	s_nop 1
	v_cndmask_b32_e32 v66, v66, v67, vcc
	v_rsq_f32_e32 v68, v66
	v_add_co_u32_e64 v66, s[6:7], s63, v146
	v_mul_f32_e32 v69, 0x45800000, v68
	v_cndmask_b32_e32 v68, v68, v69, vcc
	v_mul_f32_e32 v62, v62, v68
	v_mul_f32_e32 v63, v63, v68
	v_mul_f32_e32 v60, v60, v68
	v_mul_f32_e32 v61, v61, v68
	v_mul_f32_e32 v58, v58, v68
	v_mul_f32_e32 v59, v59, v68
	v_mul_f32_e32 v56, v56, v68
	v_mul_f32_e32 v57, v57, v68
	v_mul_f32_e32 v50, v50, v68
	v_mul_f32_e32 v51, v51, v68
	v_mul_f32_e32 v48, v48, v68
	v_mul_f32_e32 v49, v49, v68
	v_mul_f32_e32 v54, v54, v68
	v_mul_f32_e32 v55, v55, v68
	v_mul_f32_e32 v52, v52, v68
	v_mul_f32_e32 v53, v53, v68
	v_max_f32_e32 v60, 0, v60
	v_max_f32_e32 v56, 0, v56
	v_max_f32_e32 v61, 0, v61
	v_max_f32_e32 v57, 0, v57
	v_max_f32_e32 v62, 0, v62
	v_max_f32_e32 v58, 0, v58
	v_max_f32_e32 v63, 0, v63
	v_max_f32_e32 v59, 0, v59
	v_max_f32_e32 v48, 0, v48
	v_max_f32_e32 v49, 0, v49
	v_max_f32_e32 v50, 0, v50
	v_max_f32_e32 v51, 0, v51
	v_addc_co_u32_e64 v67, s[6:7], 0, v147, s[6:7]
	v_max_f32_e32 v52, 0, v52
	v_max_f32_e32 v53, 0, v53
	v_max_f32_e32 v54, 0, v54
	v_max_f32_e32 v55, 0, v55
; __device__ __forceinline__ unsigned cvt_pk_bf16(float lo, float hi) { unsigned r; asm volatile("v_cvt_pk_bf16_f32 %0, %1, %2" : "=v"(r) : "v"(lo), "v"(hi)); return r; }
;     DI void operator()(const f32x4 (&acc)[2][2][4][2], const Unit& u, int wr, int wc, int fr, int fq) const {
;         const int row0 = u.pm * 256 + wr * 64 + fr, col0 = u.pn * 256 + wc * 32 + 8 * fq;
; #pragma unroll
;         for (int ai = 0; ai < 2; ++ai)
; #pragma unroll
;             for (int m = 0; m < 4; ++m) { const int row = row0 + ai * 128 + m * 16; const float s = rsqrtf(ssum2[row] * (1.f / 1024.f) + EPS);
;                 bf16_t* rowp = U + (size_t)row * 4096 + col0;
; #pragma unroll
;                 for (int bj = 0; bj < 2; ++bj) { f32x4 v0 = acc[ai][bj][m][0] * s, v1 = acc[ai][bj][m][1] * s;
; #pragma unroll
;                     for (int j = 0; j < 4; ++j) { const float a = fmaxf(v0[j], 0.f), b = fmaxf(v1[j], 0.f); v0[j] = a * a; v1[j] = b * b; }
;                     u32x4 w; w.x = cvt_pk_bf16(v0[0], v0[1]); w.y = cvt_pk_bf16(v0[2], v0[3]); w.z = cvt_pk_bf16(v1[0], v1[1]); w.w = cvt_pk_bf16(v1[2], v1[3]);
;                     __builtin_nontemporal_store(w, (u32x4*)(rowp + bj * 128)); } }
;     }
	v_mul_f32_e32 v60, v60, v60
	v_mul_f32_e32 v56, v56, v56
	v_mul_f32_e32 v61, v61, v61
	v_mul_f32_e32 v57, v57, v57
	v_mul_f32_e32 v62, v62, v62
	v_mul_f32_e32 v58, v58, v58
	v_mul_f32_e32 v63, v63, v63
	v_mul_f32_e32 v59, v59, v59
	v_mul_f32_e32 v68, v48, v48
	v_mul_f32_e32 v69, v49, v49
	v_mul_f32_e32 v70, v50, v50
	v_mul_f32_e32 v71, v51, v51
	v_cvt_pk_bf16_f32 v48, v60, v61
	v_cvt_pk_bf16_f32 v49, v62, v63
	v_cvt_pk_bf16_f32 v50, v56, v57
	v_cvt_pk_bf16_f32 v51, v58, v59
	v_mul_f32_e32 v52, v52, v52
	v_mul_f32_e32 v53, v53, v53
	v_mul_f32_e32 v54, v54, v54
	v_mul_f32_e32 v55, v55, v55
	global_store_dwordx4 v[66:67], v[48:51], off nt
	s_nop 1
	v_cvt_pk_bf16_f32 v48, v52, v53
	v_cvt_pk_bf16_f32 v49, v54, v55
	v_cvt_pk_bf16_f32 v50, v68, v69
	v_cvt_pk_bf16_f32 v51, v70, v71
	global_store_dwordx4 v[64:65], v[48:51], off offset:256 nt
	s_nop 0
	s_nop 0
	v_lshl_add_u64 v[48:49], v[146:147], 0, s[22:23]
	s_nop 0
	v_fmamk_f32 v50, v230, 0x3a800000, v158
	v_mul_f32_e32 v51, 0x4b800000, v50
	v_cmp_gt_f32_e32 vcc, s62, v50
	s_nop 1
	v_cndmask_b32_e32 v50, v50, v51, vcc
	v_rsq_f32_e32 v52, v50
	v_add_co_u32_e64 v50, s[6:7], s64, v146
	v_mul_f32_e32 v53, 0x45800000, v52
	v_cndmask_b32_e32 v52, v52, v53, vcc
	v_mul_f32_e32 v46, v46, v52
	v_mul_f32_e32 v47, v47, v52
	v_mul_f32_e32 v44, v44, v52
	v_mul_f32_e32 v45, v45, v52
	v_mul_f32_e32 v42, v42, v52
	v_mul_f32_e32 v43, v43, v52
	v_mul_f32_e32 v40, v40, v52
	v_mul_f32_e32 v41, v41, v52
	v_mul_f32_e32 v34, v34, v52
	v_mul_f32_e32 v35, v35, v52
	v_mul_f32_e32 v32, v32, v52
	v_mul_f32_e32 v33, v33, v52
	v_mul_f32_e32 v38, v38, v52
	v_mul_f32_e32 v39, v39, v52
	v_mul_f32_e32 v36, v36, v52
	v_mul_f32_e32 v37, v37, v52
	v_max_f32_e32 v44, 0, v44
	v_max_f32_e32 v40, 0, v40
	v_max_f32_e32 v45, 0, v45
	v_max_f32_e32 v41, 0, v41
	v_max_f32_e32 v46, 0, v46
	v_max_f32_e32 v42, 0, v42
	v_max_f32_e32 v47, 0, v47
	v_max_f32_e32 v43, 0, v43
	v_max_f32_e32 v32, 0, v32
	v_max_f32_e32 v33, 0, v33
	v_max_f32_e32 v34, 0, v34
	v_max_f32_e32 v35, 0, v35
	v_addc_co_u32_e64 v51, s[6:7], 0, v147, s[6:7]
	v_max_f32_e32 v36, 0, v36
	v_max_f32_e32 v37, 0, v37
	v_max_f32_e32 v38, 0, v38
	v_max_f32_e32 v39, 0, v39
	v_mul_f32_e32 v44, v44, v44
	v_mul_f32_e32 v40, v40, v40
	v_mul_f32_e32 v45, v45, v45
	v_mul_f32_e32 v41, v41, v41
	v_mul_f32_e32 v46, v46, v46
	v_mul_f32_e32 v42, v42, v42
	v_mul_f32_e32 v47, v47, v47
	v_mul_f32_e32 v43, v43, v43
	v_mul_f32_e32 v52, v32, v32
	v_mul_f32_e32 v53, v33, v33
	v_mul_f32_e32 v54, v34, v34
	v_mul_f32_e32 v55, v35, v35
	v_cvt_pk_bf16_f32 v32, v44, v45
	v_cvt_pk_bf16_f32 v33, v46, v47
	v_cvt_pk_bf16_f32 v34, v40, v41
	v_cvt_pk_bf16_f32 v35, v42, v43
	v_mul_f32_e32 v36, v36, v36
	v_mul_f32_e32 v37, v37, v37
	v_mul_f32_e32 v38, v38, v38
	v_mul_f32_e32 v39, v39, v39
	global_store_dwordx4 v[50:51], v[32:35], off nt
	s_nop 1
	v_cvt_pk_bf16_f32 v32, v36, v37
	v_cvt_pk_bf16_f32 v33, v38, v39
	v_cvt_pk_bf16_f32 v34, v52, v53
	v_cvt_pk_bf16_f32 v35, v54, v55
	global_store_dwordx4 v[48:49], v[32:35], off offset:256 nt
	s_nop 0
	s_nop 0
	v_lshl_add_u64 v[32:33], v[146:147], 0, s[24:25]
	s_nop 0
	v_fmamk_f32 v34, v231, 0x3a800000, v158
	v_mul_f32_e32 v35, 0x4b800000, v34
	v_cmp_gt_f32_e32 vcc, s62, v34
	s_nop 1
	v_cndmask_b32_e32 v34, v34, v35, vcc
	v_rsq_f32_e32 v36, v34
	v_add_co_u32_e64 v34, s[6:7], s65, v146
	v_mul_f32_e32 v37, 0x45800000, v36
	v_cndmask_b32_e32 v36, v36, v37, vcc
	v_mul_f32_e32 v30, v30, v36
	v_mul_f32_e32 v31, v31, v36
	v_mul_f32_e32 v28, v28, v36
	v_mul_f32_e32 v29, v29, v36
	v_mul_f32_e32 v26, v26, v36
	v_mul_f32_e32 v27, v27, v36
	v_mul_f32_e32 v24, v24, v36
	v_mul_f32_e32 v25, v25, v36
	v_mul_f32_e32 v18, v18, v36
	v_mul_f32_e32 v19, v19, v36
	v_mul_f32_e32 v16, v16, v36
	v_mul_f32_e32 v17, v17, v36
; __device__ __forceinline__ unsigned cvt_pk_bf16(float lo, float hi) { unsigned r; asm volatile("v_cvt_pk_bf16_f32 %0, %1, %2" : "=v"(r) : "v"(lo), "v"(hi)); return r; }
;     DI void operator()(const f32x4 (&acc)[2][2][4][2], const Unit& u, int wr, int wc, int fr, int fq) const {
;         const int row0 = u.pm * 256 + wr * 64 + fr, col0 = u.pn * 256 + wc * 32 + 8 * fq;
; #pragma unroll
;         for (int ai = 0; ai < 2; ++ai)
; #pragma unroll
;             for (int m = 0; m < 4; ++m) { const int row = row0 + ai * 128 + m * 16; const float s = rsqrtf(ssum2[row] * (1.f / 1024.f) + EPS);
;                 bf16_t* rowp = U + (size_t)row * 4096 + col0;
; #pragma unroll
;                 for (int bj = 0; bj < 2; ++bj) { f32x4 v0 = acc[ai][bj][m][0] * s, v1 = acc[ai][bj][m][1] * s;
; #pragma unroll
;                     for (int j = 0; j < 4; ++j) { const float a = fmaxf(v0[j], 0.f), b = fmaxf(v1[j], 0.f); v0[j] = a * a; v1[j] = b * b; }
;                     u32x4 w; w.x = cvt_pk_bf16(v0[0], v0[1]); w.y = cvt_pk_bf16(v0[2], v0[3]); w.z = cvt_pk_bf16(v1[0], v1[1]); w.w = cvt_pk_bf16(v1[2], v1[3]);
;                     __builtin_nontemporal_store(w, (u32x4*)(rowp + bj * 128)); } }
;     }
	v_mul_f32_e32 v22, v22, v36
	v_mul_f32_e32 v23, v23, v36
	v_mul_f32_e32 v20, v20, v36
	v_mul_f32_e32 v21, v21, v36
	v_max_f32_e32 v28, 0, v28
	v_max_f32_e32 v24, 0, v24
	v_max_f32_e32 v29, 0, v29
	v_max_f32_e32 v25, 0, v25
	v_max_f32_e32 v30, 0, v30
	v_max_f32_e32 v26, 0, v26
	v_max_f32_e32 v31, 0, v31
	v_max_f32_e32 v27, 0, v27
	v_max_f32_e32 v16, 0, v16
	v_max_f32_e32 v17, 0, v17
	v_max_f32_e32 v18, 0, v18
	v_max_f32_e32 v19, 0, v19
	v_addc_co_u32_e64 v35, s[6:7], 0, v147, s[6:7]
	v_max_f32_e32 v20, 0, v20
	v_max_f32_e32 v21, 0, v21
	v_max_f32_e32 v22, 0, v22
	v_max_f32_e32 v23, 0, v23
	v_mul_f32_e32 v28, v28, v28
	v_mul_f32_e32 v24, v24, v24
	v_mul_f32_e32 v29, v29, v29
	v_mul_f32_e32 v25, v25, v25
	v_mul_f32_e32 v30, v30, v30
	v_mul_f32_e32 v26, v26, v26
	v_mul_f32_e32 v31, v31, v31
	v_mul_f32_e32 v27, v27, v27
	v_mul_f32_e32 v36, v16, v16
	v_mul_f32_e32 v37, v17, v17
	v_mul_f32_e32 v38, v18, v18
	v_mul_f32_e32 v39, v19, v19
	v_cvt_pk_bf16_f32 v16, v28, v29
	v_cvt_pk_bf16_f32 v17, v30, v31
	v_cvt_pk_bf16_f32 v18, v24, v25
	v_cvt_pk_bf16_f32 v19, v26, v27
	v_mul_f32_e32 v20, v20, v20
	v_mul_f32_e32 v21, v21, v21
	v_mul_f32_e32 v22, v22, v22
	v_mul_f32_e32 v23, v23, v23
	global_store_dwordx4 v[34:35], v[16:19], off nt
	s_andn2_b64 vcc, exec, s[4:5]
	s_nop 0
	v_cvt_pk_bf16_f32 v16, v20, v21
	v_cvt_pk_bf16_f32 v17, v22, v23
	v_cvt_pk_bf16_f32 v18, v36, v37
	v_cvt_pk_bf16_f32 v19, v38, v39
	global_store_dwordx4 v[32:33], v[16:19], off offset:256 nt
	s_nop 0
	s_nop 0
	v_lshl_add_u64 v[16:17], v[146:147], 0, s[26:27]
	s_nop 0
	v_fmamk_f32 v18, v232, 0x3a800000, v158
	v_mul_f32_e32 v19, 0x4b800000, v18
	v_cmp_gt_f32_e64 s[4:5], s62, v18
	s_nop 1
	v_cndmask_b32_e64 v18, v18, v19, s[4:5]
	v_rsq_f32_e32 v20, v18
	v_add_co_u32_e64 v18, s[6:7], s66, v146
	v_mul_f32_e32 v21, 0x45800000, v20
	v_cndmask_b32_e64 v20, v20, v21, s[4:5]
	v_mul_f32_e32 v14, v14, v20
	v_mul_f32_e32 v15, v15, v20
	v_mul_f32_e32 v12, v12, v20
	v_mul_f32_e32 v13, v13, v20
	v_mul_f32_e32 v10, v10, v20
	v_mul_f32_e32 v11, v11, v20
	v_mul_f32_e32 v8, v8, v20
	v_mul_f32_e32 v9, v9, v20
	v_mul_f32_e32 v2, v2, v20
	v_mul_f32_e32 v3, v3, v20
	v_mul_f32_e32 v0, v0, v20
	v_mul_f32_e32 v1, v1, v20
	v_mul_f32_e32 v6, v6, v20
	v_mul_f32_e32 v7, v7, v20
	v_mul_f32_e32 v4, v4, v20
	v_mul_f32_e32 v5, v5, v20
	v_max_f32_e32 v12, 0, v12
	v_max_f32_e32 v8, 0, v8
	v_max_f32_e32 v13, 0, v13
	v_max_f32_e32 v9, 0, v9
	v_max_f32_e32 v14, 0, v14
	v_max_f32_e32 v10, 0, v10
	v_max_f32_e32 v15, 0, v15
	v_max_f32_e32 v11, 0, v11
	v_max_f32_e32 v0, 0, v0
	v_max_f32_e32 v1, 0, v1
	v_max_f32_e32 v2, 0, v2
	v_max_f32_e32 v3, 0, v3
	v_addc_co_u32_e64 v19, s[6:7], 0, v147, s[6:7]
	v_max_f32_e32 v4, 0, v4
	v_max_f32_e32 v5, 0, v5
	v_max_f32_e32 v6, 0, v6
	v_max_f32_e32 v7, 0, v7
	v_mul_f32_e32 v12, v12, v12
	v_mul_f32_e32 v8, v8, v8
	v_mul_f32_e32 v13, v13, v13
	v_mul_f32_e32 v9, v9, v9
	v_mul_f32_e32 v14, v14, v14
	v_mul_f32_e32 v10, v10, v10
	v_mul_f32_e32 v15, v15, v15
	v_mul_f32_e32 v11, v11, v11
	v_mul_f32_e32 v20, v0, v0
	v_mul_f32_e32 v21, v1, v1
	v_mul_f32_e32 v22, v2, v2
	v_mul_f32_e32 v23, v3, v3
	v_cvt_pk_bf16_f32 v0, v12, v13
	v_cvt_pk_bf16_f32 v1, v14, v15
	v_cvt_pk_bf16_f32 v2, v8, v9
	v_cvt_pk_bf16_f32 v3, v10, v11
	s_mov_b64 s[4:5], -1
	v_mul_f32_e32 v4, v4, v4
	v_mul_f32_e32 v5, v5, v5
	v_mul_f32_e32 v6, v6, v6
	v_mul_f32_e32 v7, v7, v7
	global_store_dwordx4 v[18:19], v[0:3], off nt
	s_nop 1
	v_cvt_pk_bf16_f32 v0, v4, v5
	v_cvt_pk_bf16_f32 v1, v6, v7
	v_cvt_pk_bf16_f32 v2, v20, v21
	v_cvt_pk_bf16_f32 v3, v22, v23
	global_store_dwordx4 v[16:17], v[0:3], off offset:256 nt
	s_cbranch_vccnz .LBB0_2059
	s_andn2_b64 vcc, exec, s[8:9]
	s_cbranch_vccnz .LBB0_2058
	s_barrier
	s_branch .LBB0_2058
